# v036 + NA: removed dead negm shadow-copy set (16 v_mov per step + latch), SGPR bool VALU round-trips replaced by s_andn2
# baseline (speedup 1.0000x reference)
; template <bool NA>
; __device__ __forceinline__ void attn_unit(LAS unsigned char* lds, const bf16_t* Q, const bf16_t* Kg, const bf16_t* Kr, const bf16_t* Vt, bf16_t* O,
;                                           int h, int seqrow0, int q0, int t0, int NT, int rows, int g0, const float* rpb_h, int wid) {
;     ...
;         for (int t = 0; t < NT; t += 2) {
;             A_STEP_NA(sA0, sA1, tmA, sB0, sB1, tmB, t);
;             if (t + 1 < NT) A_STEP_NA(sB0, sB1, tmB, sA0, sA1, tmA, t + 1);
;         }
.LBB0_767:
	s_add_i32 s1, s1, 2
	s_cmp_gt_i32 s85, s81
	v_add_u32_e32 v179, 0xf8, v179
	s_cbranch_scc1 .LBB0_867

.Lna_skipV:
	s_add_i32 s74, s79, s1
	s_add_i32 s0, s74, -4
	s_add_i32 s89, s83, s1
	s_cmp_ge_i32 s0, s33
	s_cselect_b64 s[72:73], -1, 0
	s_cmp_lt_i32 s0, s88
	s_cselect_b64 s[94:95], -1, 0
	s_and_b64 s[94:95], s[72:73], s[94:95]
	s_andn2_b64 s[72:73], exec, s[94:95]
	s_andn2_b64 vcc, exec, s[94:95]
	s_cbranch_vccnz .LBB0_778
	s_mov_b64 s[94:95], -1
	s_cmp_eq_u32 s89, 4
	v_mov_b32_e32 v0, v180
	s_cbranch_scc1 .LBB0_776
	v_cmp_lt_f32_e32 vcc, s3, v180
	s_cbranch_vccz .LBB0_779
	v_max_f32_e32 v0, v180, v180
	v_max_f32_e32 v0, 0, v0
.LBB0_776:
	s_and_b64 vcc, exec, s[94:95]
	s_cbranch_vccz .LBB0_780
	v_exp_f32_e64 v4, -v0
	v_add_f32_e32 v2, v2, v0
	v_xor_b32_e32 v130, 0x80000000, v2
	v_sub_f32_e32 v63, v63, v0
	v_pk_mul_f32 v[58:59], v[58:59], v[4:5] op_sel_hi:[1,0]
	v_pk_mul_f32 v[56:57], v[56:57], v[4:5] op_sel_hi:[1,0]
	v_pk_mul_f32 v[54:55], v[54:55], v[4:5] op_sel_hi:[1,0]
	v_pk_mul_f32 v[52:53], v[52:53], v[4:5] op_sel_hi:[1,0]
	v_pk_mul_f32 v[50:51], v[50:51], v[4:5] op_sel_hi:[1,0]
	v_pk_mul_f32 v[48:49], v[48:49], v[4:5] op_sel_hi:[1,0]
	v_pk_mul_f32 v[46:47], v[46:47], v[4:5] op_sel_hi:[1,0]
	v_pk_mul_f32 v[44:45], v[44:45], v[4:5] op_sel_hi:[1,0]
	v_pk_mul_f32 v[42:43], v[42:43], v[4:5] op_sel_hi:[1,0]
	v_pk_mul_f32 v[40:41], v[40:41], v[4:5] op_sel_hi:[1,0]
	v_pk_mul_f32 v[38:39], v[38:39], v[4:5] op_sel_hi:[1,0]
	v_pk_mul_f32 v[36:37], v[36:37], v[4:5] op_sel_hi:[1,0]
	v_pk_mul_f32 v[34:35], v[34:35], v[4:5] op_sel_hi:[1,0]
	v_pk_mul_f32 v[32:33], v[32:33], v[4:5] op_sel_hi:[1,0]
	v_pk_mul_f32 v[30:31], v[30:31], v[4:5] op_sel_hi:[1,0]
	v_pk_mul_f32 v[28:29], v[28:29], v[4:5] op_sel_hi:[1,0]
	v_mul_f32_e32 v178, v178, v4
	v_sub_f32_e32 v62, v62, v0
	v_sub_f32_e32 v61, v61, v0
	v_sub_f32_e32 v60, v60, v0
	v_sub_f32_e32 v27, v27, v0
	v_sub_f32_e32 v26, v26, v0
	v_sub_f32_e32 v25, v25, v0
	v_sub_f32_e32 v24, v24, v0
	v_sub_f32_e32 v23, v23, v0
	v_sub_f32_e32 v22, v22, v0
	v_sub_f32_e32 v21, v21, v0
	v_sub_f32_e32 v20, v20, v0
	v_sub_f32_e32 v19, v19, v0
	v_sub_f32_e32 v18, v18, v0
	v_sub_f32_e32 v17, v17, v0
	v_sub_f32_e32 v16, v16, v0
	v_sub_f32_e32 v87, v87, v0
	v_sub_f32_e32 v94, v94, v0
	v_sub_f32_e32 v93, v93, v0
	v_sub_f32_e32 v92, v92, v0
	v_sub_f32_e32 v85, v85, v0
	v_sub_f32_e32 v90, v90, v0
	v_sub_f32_e32 v91, v91, v0
	v_sub_f32_e32 v88, v88, v0
	v_sub_f32_e32 v83, v83, v0
	v_sub_f32_e32 v86, v86, v0
	v_sub_f32_e32 v89, v89, v0
	v_sub_f32_e32 v84, v84, v0
	v_sub_f32_e32 v81, v81, v0
	v_sub_f32_e32 v82, v82, v0
	v_sub_f32_e32 v95, v95, v0
	v_sub_f32_e32 v80, v80, v0
	v_mov_b32_e32 v131, v130
	v_mov_b32_e32 v132, v130
	v_mov_b32_e32 v133, v130
	v_mov_b32_e32 v134, v130
	v_mov_b32_e32 v135, v130
	v_mov_b32_e32 v136, v130
	v_mov_b32_e32 v137, v130
	v_mov_b32_e32 v138, v130
	v_mov_b32_e32 v139, v130
	v_mov_b32_e32 v140, v130
	v_mov_b32_e32 v141, v130
	v_mov_b32_e32 v142, v130
	v_mov_b32_e32 v143, v130
	v_mov_b32_e32 v144, v130
	v_mov_b32_e32 v145, v130
	v_mov_b32_e32 v127, v130
	v_mov_b32_e32 v126, v130
	v_mov_b32_e32 v125, v130
	v_mov_b32_e32 v124, v130
	v_mov_b32_e32 v123, v130
	v_mov_b32_e32 v122, v130
	v_mov_b32_e32 v121, v130
	v_mov_b32_e32 v120, v130
	v_mov_b32_e32 v119, v130
	v_mov_b32_e32 v118, v130
	v_mov_b32_e32 v117, v130
	v_mov_b32_e32 v116, v130
	v_mov_b32_e32 v115, v130
	v_mov_b32_e32 v114, v130
	v_mov_b32_e32 v113, v130
	v_mov_b32_e32 v112, v130
	s_branch .LBB0_781
.LBB0_778:
	s_branch .LBB0_782
.LBB0_779:
.LBB0_780:
	v_mov_b64_e32 v[144:145], v[126:127]
	v_mov_b64_e32 v[142:143], v[124:125]
	v_mov_b64_e32 v[140:141], v[122:123]
	v_mov_b64_e32 v[138:139], v[120:121]
	v_mov_b64_e32 v[136:137], v[118:119]
	v_mov_b64_e32 v[134:135], v[116:117]
	v_mov_b64_e32 v[132:133], v[114:115]
	v_mov_b64_e32 v[130:131], v[112:113]
; __device__ __forceinline__ float max3f(float a, float b, float c) { float r; asm("v_max3_f32 %0, %1, %2, %3" : "=v"(r) : "v"(a), "v"(b), "v"(c)); return r; }
; __device__ __forceinline__ float rowmax32(const f32x16& p0, const f32x16& p1) {
;     float a = max3f(p0[0], p0[1], p1[0]), b = max3f(p0[2], p0[3], p1[1]); a = max3f(a, p1[2], p1[3]);
; #pragma unroll
;     for (int r = 4; r < 16; r += 4) { a = max3f(a, p0[r], p0[r + 1]); b = max3f(b, p0[r + 2], p0[r + 3]); a = max3f(a, p1[r], p1[r + 1]); b = max3f(b, p1[r + 2], p1[r + 3]); }
;     const float m = fmaxf(a, b);
;     auto rr = __builtin_amdgcn_permlane32_swap(__float_as_uint(m), __float_as_uint(m), false, false);
;     return fmaxf(__uint_as_float(rr[0]), __uint_as_float(rr[1]));
; }
.LBB0_781:
.LBB0_782:
	s_add_i32 s87, s1, -4
	s_add_i32 s0, s74, -3
	s_cmp_ge_i32 s0, s33
	s_cselect_b64 s[94:95], -1, 0
	s_cmp_lt_i32 s0, s88
	s_cselect_b64 s[96:97], -1, 0
	s_and_b64 s[94:95], s[94:95], s[96:97]
	s_add_i32 s0, s1, -3
	s_cmp_lt_i32 s87, s81
	s_cselect_b64 s[96:97], -1, 0
	s_and_b64 vcc, s[94:95], s[96:97]
	s_andn2_b64 vcc, exec, vcc
	s_cbranch_vccnz .LBB0_817
	s_and_b32 s90, s0, 3
	s_mulk_i32 s90, 0x3400
	v_add_u32_e32 v0, s90, v173
	ds_read_b128 v[64:67], v0 offset:4608
	ds_read_b128 v[68:71], v0
	ds_read_b128 v[72:75], v0 offset:32
	ds_read_b128 v[220:223], v0 offset:4640
	ds_read_b128 v[224:227], v0 offset:64
	ds_read_b128 v[228:231], v0 offset:4672
	ds_read_b128 v[232:235], v0 offset:96
	ds_read_b128 v[236:239], v0 offset:4704
	s_waitcnt lgkmcnt(7)
	v_mfma_f32_32x32x16_bf16 v[96:111], v[64:67], v[146:149], v[112:127]
	s_waitcnt lgkmcnt(6)
	v_mfma_f32_32x32x16_bf16 v[130:145], v[68:71], v[146:149], v[112:127]
	s_waitcnt lgkmcnt(5)
	v_mfma_f32_32x32x16_bf16 v[130:145], v[72:75], v[150:153], v[130:145]
	s_waitcnt lgkmcnt(4)
	v_mfma_f32_32x32x16_bf16 v[96:111], v[220:223], v[150:153], v[96:111]
	s_waitcnt lgkmcnt(3)
	v_mfma_f32_32x32x16_bf16 v[130:145], v[224:227], v[154:157], v[130:145]
	s_waitcnt lgkmcnt(2)
	v_mfma_f32_32x32x16_bf16 v[96:111], v[228:231], v[154:157], v[96:111]
	s_waitcnt lgkmcnt(1)
	v_mfma_f32_32x32x16_bf16 v[130:145], v[232:235], v[158:161], v[130:145]
	s_waitcnt lgkmcnt(0)
	v_mfma_f32_32x32x16_bf16 v[96:111], v[236:239], v[158:161], v[96:111]
	ds_read_b32 v0, v179 offset:128
	ds_read_b32 v64, v179
	ds_read_b32 v65, v179 offset:4
	ds_read_b32 v66, v179 offset:8
	ds_read_b32 v67, v179 offset:12
	ds_read_b32 v68, v179 offset:32
	ds_read_b32 v69, v179 offset:36
	ds_read_b32 v70, v179 offset:40
	ds_read_b32 v71, v179 offset:44
	ds_read_b32 v72, v179 offset:64
	ds_read_b32 v73, v179 offset:68
	ds_read_b32 v74, v179 offset:72
	ds_read_b32 v75, v179 offset:76
	ds_read_b32 v76, v179 offset:96
	ds_read_b32 v77, v179 offset:100
	ds_read_b32 v78, v179 offset:104
	ds_read_b32 v79, v179 offset:108
	s_waitcnt lgkmcnt(0)
	v_add_f32_e32 v64, v130, v64
	v_cndmask_b32_e64 v64, v177, v64, s[6:7]
	v_add_f32_e32 v65, v131, v65
	v_cndmask_b32_e64 v65, v177, v65, s[10:11]
	v_add_f32_e32 v66, v132, v66
	v_cndmask_b32_e64 v66, v177, v66, s[14:15]
	v_add_f32_e32 v67, v133, v67
	v_cndmask_b32_e64 v67, v177, v67, s[18:19]
	v_add_f32_e32 v68, v134, v68
	v_cndmask_b32_e64 v68, v177, v68, s[22:23]
	v_add_f32_e32 v69, v135, v69
	v_cndmask_b32_e64 v69, v177, v69, s[26:27]
	v_add_f32_e32 v70, v136, v70
	v_cndmask_b32_e64 v70, v177, v70, s[30:31]
	v_add_f32_e32 v71, v137, v71
	v_cndmask_b32_e64 v71, v177, v71, s[36:37]
	v_add_f32_e32 v72, v138, v72
	v_cndmask_b32_e64 v72, v177, v72, s[40:41]
	v_add_f32_e32 v73, v139, v73
	v_cndmask_b32_e64 v73, v177, v73, s[44:45]
	v_add_f32_e32 v74, v140, v74
	v_cndmask_b32_e64 v74, v177, v74, s[48:49]
	v_add_f32_e32 v75, v141, v75
	v_cndmask_b32_e64 v75, v177, v75, s[52:53]
	v_add_f32_e32 v76, v142, v76
	v_cndmask_b32_e64 v76, v177, v76, s[56:57]
	v_add_f32_e32 v77, v143, v77
	v_cndmask_b32_e64 v77, v177, v77, s[60:61]
	v_add_f32_e32 v78, v144, v78
	v_cndmask_b32_e64 v78, v177, v78, s[64:65]
	v_add_f32_e32 v79, v145, v79
	v_cndmask_b32_e64 v79, v177, v79, s[68:69]
	ds_read_b32 v3, v179 offset:132
	ds_read_b32 v129, v179 offset:136
	ds_read_b32 v130, v179 offset:140
	ds_read_b32 v131, v179 offset:160
	ds_read_b32 v132, v179 offset:164
	ds_read_b32 v133, v179 offset:168
	ds_read_b32 v134, v179 offset:172
	ds_read_b32 v135, v179 offset:192
	ds_read_b32 v136, v179 offset:196
	ds_read_b32 v137, v179 offset:200
	ds_read_b32 v138, v179 offset:204
	ds_read_b32 v139, v179 offset:224
	ds_read_b32 v140, v179 offset:228
	ds_read_b32 v142, v179 offset:232
	ds_read_b32 v141, v179 offset:236
	s_waitcnt lgkmcnt(14)
	v_add_f32_e32 v0, v96, v0
	v_cndmask_b32_e64 v96, v177, v0, s[8:9]
	v_add_f32_e32 v0, v97, v3
	v_cndmask_b32_e64 v97, v177, v0, s[12:13]
	s_waitcnt lgkmcnt(13)
	v_add_f32_e32 v0, v98, v129
	v_cndmask_b32_e64 v98, v177, v0, s[16:17]
	s_waitcnt lgkmcnt(12)
	v_add_f32_e32 v0, v99, v130
	v_cndmask_b32_e64 v99, v177, v0, s[20:21]
	s_waitcnt lgkmcnt(11)
	v_add_f32_e32 v0, v100, v131
	v_cndmask_b32_e64 v100, v177, v0, s[24:25]
	s_waitcnt lgkmcnt(10)
	v_add_f32_e32 v0, v101, v132
	v_cndmask_b32_e64 v101, v177, v0, s[28:29]
	s_waitcnt lgkmcnt(9)
	v_add_f32_e32 v0, v102, v133
	v_cndmask_b32_e64 v102, v177, v0, s[34:35]
	s_waitcnt lgkmcnt(8)
	v_add_f32_e32 v0, v103, v134
	v_cndmask_b32_e64 v103, v177, v0, s[38:39]
	s_waitcnt lgkmcnt(7)
	v_add_f32_e32 v0, v104, v135
	v_cndmask_b32_e64 v104, v177, v0, s[42:43]
	s_waitcnt lgkmcnt(6)
	v_add_f32_e32 v0, v105, v136
	v_cndmask_b32_e64 v105, v177, v0, s[46:47]
	s_waitcnt lgkmcnt(5)
	v_add_f32_e32 v0, v106, v137
	v_cndmask_b32_e64 v106, v177, v0, s[50:51]
	s_waitcnt lgkmcnt(4)
	v_add_f32_e32 v0, v107, v138
	v_cndmask_b32_e64 v107, v177, v0, s[54:55]
	s_waitcnt lgkmcnt(3)
	v_add_f32_e32 v0, v108, v139
	v_cndmask_b32_e64 v108, v177, v0, s[58:59]
	s_waitcnt lgkmcnt(2)
	v_add_f32_e32 v0, v109, v140
	v_cndmask_b32_e64 v109, v177, v0, s[62:63]
	s_waitcnt lgkmcnt(1)
	v_add_f32_e32 v0, v110, v142
	v_cndmask_b32_e64 v110, v177, v0, s[66:67]
	s_waitcnt lgkmcnt(0)
	v_add_f32_e32 v0, v111, v141
	v_cndmask_b32_e64 v111, v177, v0, s[70:71]
	v_max3_f32 v0, v64, v65, v96
	v_max3_f32 v3, v66, v67, v97
	v_max3_f32 v0, v0, v98, v99
	v_max3_f32 v3, v3, v70, v71
	v_max3_f32 v0, v0, v68, v69
	v_max3_f32 v3, v3, v102, v103
	v_max3_f32 v0, v0, v100, v101
	v_max3_f32 v3, v3, v74, v75
	v_max3_f32 v0, v0, v72, v73
	v_max3_f32 v3, v3, v106, v107
	v_max3_f32 v0, v0, v104, v105
	v_max3_f32 v3, v3, v78, v79
	v_max3_f32 v0, v0, v76, v77
	v_max3_f32 v3, v3, v110, v111
	v_max3_f32 v0, v0, v108, v109
	v_max_f32_e32 v0, v0, v3
	v_mov_b32_e32 v3, v0
	s_nop 1
	v_permlane32_swap_b32_e32 v0, v3
	v_max_f32_e32 v3, v0, v3
	s_and_b64 vcc, exec, s[72:73]
	s_cbranch_vccz .LBB0_818

.LBB0_819:
.LBB0_823:
	s_andn2_b64 s[72:73], exec, s[94:95]
	s_andn2_b64 vcc, exec, s[94:95]
	s_cbranch_vccnz .LBB0_829
	s_mov_b64 s[94:95], -1
	s_cmp_eq_u32 s89, 3
	v_mov_b32_e32 v0, v3
	s_cbranch_scc1 .LBB0_827
	v_cmp_lt_f32_e32 vcc, s3, v3
	s_cbranch_vccz .LBB0_866
	v_max_f32_e32 v0, v3, v3
	v_max_f32_e32 v0, 0, v0
